# moba non-diagonal steps: hand-interleaved fused step (S-MFMAs for next tile interleaved with softmax VALU and PV MFMAs; permlane32_swap instead of ds_bpermute)
# speedup vs baseline: 1.0119x; 1.0119x over previous
.LBB0_611:
	s_add_i32 s0, s14, -5
	s_add_i32 s1, s15, 1
	s_cmp_lg_u32 s15, 2
	s_cselect_b32 s17, s1, 0
	s_add_i32 s1, s14, -4
	s_cmp_lt_u32 s1, s85
	s_cselect_b64 s[8:9], -1, 0
	s_lshr_b32 s16, s0, 2
	s_lshl_b32 s18, s16, 8
	s_cmp_ge_u32 s1, s85
	s_cbranch_scc1 .LBB0_620
	s_cmp_lg_u32 s16, s84
	s_cbranch_scc1 .Lmoba_fuse_a
	s_sub_i32 s0, s13, 64
	s_and_b32 s0, s0, 0xc0
	s_or_b32 s6, s0, s18
	v_cmp_le_i32_e32 vcc, s6, v214
	s_and_saveexec_b64 s[10:11], vcc
	s_cbranch_execz .LBB0_619
	s_lshl_b32 s0, s17, 13
	s_mov_b64 s[4:5], -1
	s_cmp_lg_u32 s16, s84
	v_add_u32_e32 v36, s0, v204
	v_add_u32_e32 v35, s0, v205
	v_add_u32_e32 v34, s0, v206
	v_add_u32_e32 v32, s0, v208
	s_cbranch_scc0 .LBB0_615
	ds_read_b128 v[38:41], v36 offset:4096
	ds_read_b128 v[42:45], v36 offset:8192
	s_mov_b64 s[4:5], 0
	s_waitcnt lgkmcnt(1)
	v_mfma_f32_32x32x16_bf16 v[96:111], v[38:41], v[128:131], 0
	ds_read_b128 v[38:41], v35 offset:4096
	ds_read_b128 v[218:221], v35 offset:8192
	s_waitcnt lgkmcnt(2)
	v_mfma_f32_32x32x16_bf16 v[112:127], v[42:45], v[128:131], 0
	s_waitcnt lgkmcnt(1)
	v_mfma_f32_32x32x16_bf16 v[96:111], v[38:41], v[132:135], v[96:111]
	ds_read_b128 v[38:41], v34 offset:4096
	ds_read_b128 v[222:225], v34 offset:8192
	s_waitcnt lgkmcnt(2)
	v_mfma_f32_32x32x16_bf16 v[112:127], v[218:221], v[132:135], v[112:127]
	s_waitcnt lgkmcnt(1)
	v_mfma_f32_32x32x16_bf16 v[96:111], v[38:41], v[136:139], v[96:111]
	ds_read_b128 v[38:41], v32 offset:4096
	ds_read_b128 v[226:229], v32 offset:8192
	s_waitcnt lgkmcnt(2)
	v_mfma_f32_32x32x16_bf16 v[112:127], v[222:225], v[136:139], v[112:127]
	s_waitcnt lgkmcnt(1)
	v_mfma_f32_32x32x16_bf16 v[96:111], v[38:41], v[140:143], v[96:111]
	s_waitcnt lgkmcnt(0)
	v_mfma_f32_32x32x16_bf16 v[112:127], v[226:229], v[140:143], v[112:127]

.LBB0_624:
	s_or_b64 exec, exec, s[6:7]
	s_add_i32 s0, s17, 1
	s_cmp_lg_u32 s17, 2
	s_cselect_b32 s19, s0, 0
	s_add_i32 s0, s14, -1
	s_lshl_b32 s7, s19, 13
	s_min_i32 s0, s0, s12
	v_add_u32_e32 v32, s7, v209
	s_lshl_b32 s0, s0, 6
	v_add_u32_e32 v34, v32, v210
	v_add3_u32 v35, v32, v212, v211
	s_ashr_i32 s1, s0, 31
	s_waitcnt vmcnt(3)
	ds_write_b128 v34, v[148:151] offset:4096
	v_add3_u32 v32, v32, v213, v211
	s_waitcnt vmcnt(2)
	ds_write_b128 v34, v[156:159] offset:8192
	s_waitcnt vmcnt(0)
	ds_write2st64_b64 v35, v[144:145], v[152:153] offset0:56 offset1:64
	ds_write2st64_b64 v32, v[146:147], v[154:155] offset0:56 offset1:64
	v_lshl_add_u64 v[34:35], v[186:187], 0, s[0:1]
	v_mad_u64_u32 v[36:37], s[4:5], v34, s81, v[194:195]
	s_lshl_b64 s[4:5], s[0:1], 1
	v_lshl_add_u64 v[38:39], v[190:191], 0, s[0:1]
	v_mad_i32_i24 v37, v35, s81, v37
	v_lshl_add_u64 v[34:35], v[188:189], 0, s[4:5]
	v_mad_u64_u32 v[40:41], s[0:1], v38, s81, v[194:195]
	v_mad_i32_i24 v41, v39, s81, v41
	global_load_dwordx4 v[148:151], v[36:37], off offset:1024
	global_load_dwordx4 v[156:159], v[40:41], off offset:1024
	v_lshl_add_u64 v[36:37], v[192:193], 0, s[4:5]
	global_load_dwordx4 v[144:147], v[34:35], off
	global_load_dwordx4 v[152:155], v[36:37], off
	s_andn2_b64 vcc, exec, s[8:9]
	s_waitcnt lgkmcnt(0)
	s_barrier
	s_cbranch_vccnz .LBB0_641
	s_add_i32 s4, s14, -3
	s_cmp_ge_u32 s4, s85
	s_cbranch_scc1 .LBB0_636
	s_lshr_b32 s8, s4, 2
	s_cmp_lg_u32 s8, s84
	s_cbranch_scc1 .Lmoba_fuse_b
	s_lshl_b32 s0, s8, 8
	s_and_b32 s1, s13, 0x80
	s_or_b32 s6, s0, s1
	v_cmp_le_i32_e32 vcc, s6, v214
	s_and_saveexec_b64 s[10:11], vcc
	s_cbranch_execz .LBB0_635
	s_mov_b64 s[4:5], -1
	s_cmp_lg_u32 s8, s84
	v_add_u32_e32 v36, s7, v204
	v_add_u32_e32 v35, s7, v205
	v_add_u32_e32 v34, s7, v206
	v_add_u32_e32 v32, s7, v208
	s_cbranch_scc0 .LBB0_629
	ds_read_b128 v[0:3], v36 offset:4096
	ds_read_b128 v[16:19], v36 offset:8192
	ds_read_b128 v[20:23], v35 offset:4096
	ds_read_b128 v[38:41], v35 offset:8192
	s_mov_b64 s[4:5], 0
	s_waitcnt lgkmcnt(3)
	v_mfma_f32_32x32x16_bf16 v[0:15], v[0:3], v[128:131], 0
	s_waitcnt lgkmcnt(1)
	v_mfma_f32_32x32x16_bf16 v[0:15], v[20:23], v[132:135], v[0:15]
	ds_read_b128 v[20:23], v34 offset:4096
	ds_read_b128 v[42:45], v34 offset:8192
	s_waitcnt lgkmcnt(1)
	v_mfma_f32_32x32x16_bf16 v[0:15], v[20:23], v[136:139], v[0:15]
	ds_read_b128 v[20:23], v32 offset:4096
	ds_read_b128 v[218:221], v32 offset:8192
	s_waitcnt lgkmcnt(1)
	v_mfma_f32_32x32x16_bf16 v[0:15], v[20:23], v[140:143], v[0:15]
	v_mfma_f32_32x32x16_bf16 v[16:31], v[16:19], v[128:131], 0
	v_mfma_f32_32x32x16_bf16 v[16:31], v[38:41], v[132:135], v[16:31]
	v_mfma_f32_32x32x16_bf16 v[16:31], v[42:45], v[136:139], v[16:31]
	s_waitcnt lgkmcnt(0)
	v_mfma_f32_32x32x16_bf16 v[16:31], v[218:221], v[140:143], v[16:31]

.Lmoba_fuse_a:
	s_lshl_b32 s0, s17, 13
	s_lshl_b32 s1, s15, 13
	v_add_u32_e32 v230, s0, v204
	v_add_u32_e32 v231, s0, v205
	v_add_u32_e32 v232, s0, v206
	v_add_u32_e32 v233, s0, v208
	ds_read_b128 v[218:221], v230 offset:4096
	ds_read_b128 v[222:225], v230 offset:8192
	ds_read_b128 v[226:229], v231 offset:4096
	ds_read_b128 v[234:237], v231 offset:8192
	ds_read_b128 v[238:241], v232 offset:4096
	ds_read_b128 v[242:245], v232 offset:8192
	ds_read_b128 v[246:249], v233 offset:4096
	ds_read_b128 v[250:253], v233 offset:8192
	v_add_u32_e32 v230, s1, v204
	v_add_u32_e32 v231, s1, v205
	v_add_u32_e32 v232, s1, v206
	v_add_u32_e32 v233, s1, v208
	ds_read_b128 v[34:37], v230 offset:28672
	ds_read_b128 v[42:45], v230 offset:32768
	v_max_f32_e32 v32, v1, v1
	v_max_f32_e32 v217, v0, v0
	v_max_f32_e32 v32, v217, v32
	v_max3_f32 v32, v32, v2, v3
	v_max3_f32 v32, v32, v4, v5
	v_max3_f32 v32, v32, v6, v7
	v_max3_f32 v32, v32, v8, v9
	v_max3_f32 v32, v32, v10, v11
	v_max3_f32 v32, v32, v12, v13
	v_max3_f32 v32, v32, v14, v15
	s_waitcnt lgkmcnt(9)
	v_mfma_f32_32x32x16_bf16 v[96:111], v[218:221], v[128:131], 0
	v_max3_f32 v32, v32, v16, v17
	v_max3_f32 v32, v32, v18, v19
	v_max3_f32 v32, v32, v20, v21
	v_max3_f32 v32, v32, v22, v23
	v_max3_f32 v32, v32, v24, v25
	v_max3_f32 v32, v32, v26, v27
	s_waitcnt lgkmcnt(8)
	v_mfma_f32_32x32x16_bf16 v[112:127], v[222:225], v[128:131], 0
	ds_read_b128 v[218:221], v231 offset:28672
	ds_read_b128 v[222:225], v231 offset:32768
	v_max3_f32 v32, v32, v28, v29
	v_max3_f32 v32, v32, v30, v31
	v_mov_b32_e32 v217, v32
	s_lshl_b32 s4, 1, s16
	v_and_b32_e32 v254, s4, v203
	v_permlane32_swap_b32_e32 v217, v32
	v_cmp_ne_u32_e32 vcc, 0, v254
	v_max_f32_e32 v217, v217, v217
	v_max_f32_e32 v32, v32, v217
	s_waitcnt lgkmcnt(9)
	v_mfma_f32_32x32x16_bf16 v[96:111], v[226:229], v[132:135], v[96:111]
	v_cndmask_b32_e32 v32, v199, v32, vcc
	v_max_f32_e32 v217, v216, v216
	v_max_f32_e32 v32, v217, v32
	v_sub_f32_e32 v217, v216, v32
	v_cmp_lt_f32_e64 s[4:5], s82, v32
	v_mul_f32_e32 v217, 0x3e38aa3b, v217
	v_mul_f32_e32 v254, 0xbe38aa3b, v32
	s_and_b64 vcc, vcc, s[4:5]
	s_waitcnt lgkmcnt(8)
	v_mfma_f32_32x32x16_bf16 v[112:127], v[234:237], v[132:135], v[112:127]
	ds_read_b128 v[226:229], v232 offset:28672
	ds_read_b128 v[234:237], v232 offset:32768
	v_exp_f32_e32 v46, v217
	v_cndmask_b32_e32 v47, v199, v254, vcc
	v_mov_b32_e32 v216, v32
	v_fmamk_f32 v0, v0, 0x3e38aa3b, v47
	v_fmamk_f32 v1, v1, 0x3e38aa3b, v47
	v_fmamk_f32 v2, v2, 0x3e38aa3b, v47
	v_fmamk_f32 v3, v3, 0x3e38aa3b, v47
	v_fmamk_f32 v4, v4, 0x3e38aa3b, v47
	v_fmamk_f32 v5, v5, 0x3e38aa3b, v47
	v_fmamk_f32 v6, v6, 0x3e38aa3b, v47
	v_fmamk_f32 v7, v7, 0x3e38aa3b, v47
	s_waitcnt lgkmcnt(9)
	v_mfma_f32_32x32x16_bf16 v[96:111], v[238:241], v[136:139], v[96:111]
	v_exp_f32_e32 v0, v0
	v_exp_f32_e32 v1, v1
	v_exp_f32_e32 v2, v2
	v_exp_f32_e32 v3, v3
	s_waitcnt lgkmcnt(8)
	v_mfma_f32_32x32x16_bf16 v[112:127], v[242:245], v[136:139], v[112:127]
	ds_read_b128 v[238:241], v233 offset:28672
	ds_read_b128 v[242:245], v233 offset:32768
	v_exp_f32_e32 v4, v4
	v_exp_f32_e32 v5, v5
	v_exp_f32_e32 v6, v6
	v_exp_f32_e32 v7, v7
	s_waitcnt lgkmcnt(9)
	v_mfma_f32_32x32x16_bf16 v[96:111], v[246:249], v[140:143], v[96:111]
	v_pk_mul_f32 v[64:65], v[64:65], v[46:47] op_sel_hi:[1,0]
	v_pk_mul_f32 v[66:67], v[66:67], v[46:47] op_sel_hi:[1,0]
	v_pk_mul_f32 v[68:69], v[68:69], v[46:47] op_sel_hi:[1,0]
	v_pk_mul_f32 v[70:71], v[70:71], v[46:47] op_sel_hi:[1,0]
	v_pk_mul_f32 v[72:73], v[72:73], v[46:47] op_sel_hi:[1,0]
	v_pk_mul_f32 v[74:75], v[74:75], v[46:47] op_sel_hi:[1,0]
	v_pk_mul_f32 v[76:77], v[76:77], v[46:47] op_sel_hi:[1,0]
	v_pk_mul_f32 v[78:79], v[78:79], v[46:47] op_sel_hi:[1,0]
	s_waitcnt lgkmcnt(8)
	v_mfma_f32_32x32x16_bf16 v[112:127], v[250:253], v[140:143], v[112:127]
	v_pk_mul_f32 v[48:49], v[48:49], v[46:47] op_sel_hi:[1,0]
	v_pk_mul_f32 v[50:51], v[50:51], v[46:47] op_sel_hi:[1,0]
	v_pk_mul_f32 v[52:53], v[52:53], v[46:47] op_sel_hi:[1,0]
	v_pk_mul_f32 v[54:55], v[54:55], v[46:47] op_sel_hi:[1,0]
	v_pk_mul_f32 v[56:57], v[56:57], v[46:47] op_sel_hi:[1,0]
	v_pk_mul_f32 v[58:59], v[58:59], v[46:47] op_sel_hi:[1,0]
	v_pk_mul_f32 v[60:61], v[60:61], v[46:47] op_sel_hi:[1,0]
	v_pk_mul_f32 v[62:63], v[62:63], v[46:47] op_sel_hi:[1,0]
	v_mul_f32_e32 v80, v80, v46
	v_cvt_pk_bf16_f32 v38, v0, v1
	v_cvt_pk_bf16_f32 v39, v2, v3
	v_cvt_pk_bf16_f32 v40, v4, v5
	v_cvt_pk_bf16_f32 v41, v6, v7
	v_fmamk_f32 v8, v8, 0x3e38aa3b, v47
	v_fmamk_f32 v9, v9, 0x3e38aa3b, v47
	s_waitcnt lgkmcnt(7)
	v_mfma_f32_32x32x16_bf16 v[64:79], v[34:37], v[38:41], v[64:79]
	v_fmamk_f32 v10, v10, 0x3e38aa3b, v47
	v_fmamk_f32 v11, v11, 0x3e38aa3b, v47
	v_fmamk_f32 v12, v12, 0x3e38aa3b, v47
	v_fmamk_f32 v13, v13, 0x3e38aa3b, v47
	v_fmamk_f32 v14, v14, 0x3e38aa3b, v47
	v_fmamk_f32 v15, v15, 0x3e38aa3b, v47
	v_exp_f32_e32 v8, v8
	s_waitcnt lgkmcnt(6)
	v_mfma_f32_32x32x16_bf16 v[48:63], v[42:45], v[38:41], v[48:63]
	v_exp_f32_e32 v9, v9
	v_exp_f32_e32 v10, v10
	v_mfma_f32_32x32x16_bf16 v[80:95], v[176:179], v[38:41], v[80:95]
	v_exp_f32_e32 v11, v11
	v_exp_f32_e32 v12, v12
	v_exp_f32_e32 v13, v13
	v_exp_f32_e32 v14, v14
	v_exp_f32_e32 v15, v15
	v_cvt_pk_bf16_f32 v38, v8, v9
	v_cvt_pk_bf16_f32 v39, v10, v11
	v_cvt_pk_bf16_f32 v40, v12, v13
	v_cvt_pk_bf16_f32 v41, v14, v15
	v_fmamk_f32 v16, v16, 0x3e38aa3b, v47
	v_fmamk_f32 v17, v17, 0x3e38aa3b, v47
	s_waitcnt lgkmcnt(5)
	v_mfma_f32_32x32x16_bf16 v[64:79], v[218:221], v[38:41], v[64:79]
	v_fmamk_f32 v18, v18, 0x3e38aa3b, v47
	v_fmamk_f32 v19, v19, 0x3e38aa3b, v47
	v_fmamk_f32 v20, v20, 0x3e38aa3b, v47
	v_fmamk_f32 v21, v21, 0x3e38aa3b, v47
	v_fmamk_f32 v22, v22, 0x3e38aa3b, v47
	v_fmamk_f32 v23, v23, 0x3e38aa3b, v47
	v_exp_f32_e32 v16, v16
	s_waitcnt lgkmcnt(4)
	v_mfma_f32_32x32x16_bf16 v[48:63], v[222:225], v[38:41], v[48:63]
	v_exp_f32_e32 v17, v17
	v_exp_f32_e32 v18, v18
	v_mfma_f32_32x32x16_bf16 v[80:95], v[176:179], v[38:41], v[80:95]
	v_exp_f32_e32 v19, v19
	v_exp_f32_e32 v20, v20
	v_exp_f32_e32 v21, v21
	v_exp_f32_e32 v22, v22
	v_exp_f32_e32 v23, v23
	v_cvt_pk_bf16_f32 v38, v16, v17
	v_cvt_pk_bf16_f32 v39, v18, v19
	v_cvt_pk_bf16_f32 v40, v20, v21
	v_cvt_pk_bf16_f32 v41, v22, v23
	v_fmamk_f32 v24, v24, 0x3e38aa3b, v47
	v_fmamk_f32 v25, v25, 0x3e38aa3b, v47
	s_waitcnt lgkmcnt(3)
	v_mfma_f32_32x32x16_bf16 v[64:79], v[226:229], v[38:41], v[64:79]
	v_fmamk_f32 v26, v26, 0x3e38aa3b, v47
	v_fmamk_f32 v27, v27, 0x3e38aa3b, v47
	v_fmamk_f32 v28, v28, 0x3e38aa3b, v47
	v_fmamk_f32 v29, v29, 0x3e38aa3b, v47
	v_fmamk_f32 v30, v30, 0x3e38aa3b, v47
	v_fmamk_f32 v31, v31, 0x3e38aa3b, v47
	v_exp_f32_e32 v24, v24
	s_waitcnt lgkmcnt(2)
	v_mfma_f32_32x32x16_bf16 v[48:63], v[234:237], v[38:41], v[48:63]
	v_exp_f32_e32 v25, v25
	v_exp_f32_e32 v26, v26
	v_mfma_f32_32x32x16_bf16 v[80:95], v[176:179], v[38:41], v[80:95]
	v_exp_f32_e32 v27, v27
	v_exp_f32_e32 v28, v28
	v_exp_f32_e32 v29, v29
	v_exp_f32_e32 v30, v30
	v_exp_f32_e32 v31, v31
	v_cvt_pk_bf16_f32 v38, v24, v25
	v_cvt_pk_bf16_f32 v39, v26, v27
	v_cvt_pk_bf16_f32 v40, v28, v29
	v_cvt_pk_bf16_f32 v41, v30, v31
	s_nop 1
	s_waitcnt lgkmcnt(1)
	v_mfma_f32_32x32x16_bf16 v[64:79], v[238:241], v[38:41], v[64:79]
	s_waitcnt lgkmcnt(0)
	v_mfma_f32_32x32x16_bf16 v[48:63], v[242:245], v[38:41], v[48:63]
	v_mfma_f32_32x32x16_bf16 v[80:95], v[176:179], v[38:41], v[80:95]
	s_branch .LBB0_624
.Lmoba_fuse_b:
	s_mov_b32 s0, s7
	s_lshl_b32 s1, s17, 13
	v_add_u32_e32 v230, s0, v204
	v_add_u32_e32 v231, s0, v205
	v_add_u32_e32 v232, s0, v206
	v_add_u32_e32 v233, s0, v208
	ds_read_b128 v[218:221], v230 offset:4096
	ds_read_b128 v[222:225], v230 offset:8192
	ds_read_b128 v[226:229], v231 offset:4096
	ds_read_b128 v[234:237], v231 offset:8192
	ds_read_b128 v[238:241], v232 offset:4096
	ds_read_b128 v[242:245], v232 offset:8192
	ds_read_b128 v[246:249], v233 offset:4096
	ds_read_b128 v[250:253], v233 offset:8192
	v_add_u32_e32 v230, s1, v204
	v_add_u32_e32 v231, s1, v205
	v_add_u32_e32 v232, s1, v206
	v_add_u32_e32 v233, s1, v208
	ds_read_b128 v[34:37], v230 offset:28672
	ds_read_b128 v[42:45], v230 offset:32768
	v_max_f32_e32 v32, v97, v97
	v_max_f32_e32 v217, v96, v96
	v_max_f32_e32 v32, v217, v32
	v_max3_f32 v32, v32, v98, v99
	v_max3_f32 v32, v32, v100, v101
	v_max3_f32 v32, v32, v102, v103
	v_max3_f32 v32, v32, v104, v105
	v_max3_f32 v32, v32, v106, v107
	v_max3_f32 v32, v32, v108, v109
	v_max3_f32 v32, v32, v110, v111
	s_waitcnt lgkmcnt(9)
	v_mfma_f32_32x32x16_bf16 v[0:15], v[218:221], v[128:131], 0
	v_max3_f32 v32, v32, v112, v113
	v_max3_f32 v32, v32, v114, v115
	v_max3_f32 v32, v32, v116, v117
	v_max3_f32 v32, v32, v118, v119
	v_max3_f32 v32, v32, v120, v121
	v_max3_f32 v32, v32, v122, v123
	s_waitcnt lgkmcnt(8)
	v_mfma_f32_32x32x16_bf16 v[16:31], v[222:225], v[128:131], 0
	ds_read_b128 v[218:221], v231 offset:28672
	ds_read_b128 v[222:225], v231 offset:32768
	v_max3_f32 v32, v32, v124, v125
	v_max3_f32 v32, v32, v126, v127
	v_mov_b32_e32 v217, v32
	s_lshl_b32 s4, 1, s16
	v_and_b32_e32 v254, s4, v203
	v_permlane32_swap_b32_e32 v217, v32
	v_cmp_ne_u32_e32 vcc, 0, v254
	v_max_f32_e32 v217, v217, v217
	v_max_f32_e32 v32, v32, v217
	s_waitcnt lgkmcnt(9)
	v_mfma_f32_32x32x16_bf16 v[0:15], v[226:229], v[132:135], v[0:15]
	v_cndmask_b32_e32 v32, v199, v32, vcc
	v_max_f32_e32 v217, v216, v216
	v_max_f32_e32 v32, v217, v32
	v_sub_f32_e32 v217, v216, v32
	v_cmp_lt_f32_e64 s[4:5], s82, v32
	v_mul_f32_e32 v217, 0x3e38aa3b, v217
	v_mul_f32_e32 v254, 0xbe38aa3b, v32
	s_and_b64 vcc, vcc, s[4:5]
	s_waitcnt lgkmcnt(8)
	v_mfma_f32_32x32x16_bf16 v[16:31], v[234:237], v[132:135], v[16:31]
	ds_read_b128 v[226:229], v232 offset:28672
	ds_read_b128 v[234:237], v232 offset:32768
	v_exp_f32_e32 v46, v217
	v_cndmask_b32_e32 v47, v199, v254, vcc
	v_mov_b32_e32 v216, v32
	v_fmamk_f32 v96, v96, 0x3e38aa3b, v47
	v_fmamk_f32 v97, v97, 0x3e38aa3b, v47
	v_fmamk_f32 v98, v98, 0x3e38aa3b, v47
	v_fmamk_f32 v99, v99, 0x3e38aa3b, v47
	v_fmamk_f32 v100, v100, 0x3e38aa3b, v47
	v_fmamk_f32 v101, v101, 0x3e38aa3b, v47
	v_fmamk_f32 v102, v102, 0x3e38aa3b, v47
	v_fmamk_f32 v103, v103, 0x3e38aa3b, v47
	s_waitcnt lgkmcnt(9)
	v_mfma_f32_32x32x16_bf16 v[0:15], v[238:241], v[136:139], v[0:15]
	v_exp_f32_e32 v96, v96
	v_exp_f32_e32 v97, v97
	v_exp_f32_e32 v98, v98
	v_exp_f32_e32 v99, v99
	s_waitcnt lgkmcnt(8)
	v_mfma_f32_32x32x16_bf16 v[16:31], v[242:245], v[136:139], v[16:31]
	ds_read_b128 v[238:241], v233 offset:28672
	ds_read_b128 v[242:245], v233 offset:32768
	v_exp_f32_e32 v100, v100
	v_exp_f32_e32 v101, v101
	v_exp_f32_e32 v102, v102
	v_exp_f32_e32 v103, v103
	s_waitcnt lgkmcnt(9)
	v_mfma_f32_32x32x16_bf16 v[0:15], v[246:249], v[140:143], v[0:15]
	v_pk_mul_f32 v[64:65], v[64:65], v[46:47] op_sel_hi:[1,0]
	v_pk_mul_f32 v[66:67], v[66:67], v[46:47] op_sel_hi:[1,0]
	v_pk_mul_f32 v[68:69], v[68:69], v[46:47] op_sel_hi:[1,0]
	v_pk_mul_f32 v[70:71], v[70:71], v[46:47] op_sel_hi:[1,0]
	v_pk_mul_f32 v[72:73], v[72:73], v[46:47] op_sel_hi:[1,0]
	v_pk_mul_f32 v[74:75], v[74:75], v[46:47] op_sel_hi:[1,0]
	v_pk_mul_f32 v[76:77], v[76:77], v[46:47] op_sel_hi:[1,0]
	v_pk_mul_f32 v[78:79], v[78:79], v[46:47] op_sel_hi:[1,0]
	s_waitcnt lgkmcnt(8)
	v_mfma_f32_32x32x16_bf16 v[16:31], v[250:253], v[140:143], v[16:31]
	v_pk_mul_f32 v[48:49], v[48:49], v[46:47] op_sel_hi:[1,0]
	v_pk_mul_f32 v[50:51], v[50:51], v[46:47] op_sel_hi:[1,0]
	v_pk_mul_f32 v[52:53], v[52:53], v[46:47] op_sel_hi:[1,0]
	v_pk_mul_f32 v[54:55], v[54:55], v[46:47] op_sel_hi:[1,0]
	v_pk_mul_f32 v[56:57], v[56:57], v[46:47] op_sel_hi:[1,0]
	v_pk_mul_f32 v[58:59], v[58:59], v[46:47] op_sel_hi:[1,0]
	v_pk_mul_f32 v[60:61], v[60:61], v[46:47] op_sel_hi:[1,0]
	v_pk_mul_f32 v[62:63], v[62:63], v[46:47] op_sel_hi:[1,0]
	v_mul_f32_e32 v80, v80, v46
	v_cvt_pk_bf16_f32 v38, v96, v97
	v_cvt_pk_bf16_f32 v39, v98, v99
	v_cvt_pk_bf16_f32 v40, v100, v101
	v_cvt_pk_bf16_f32 v41, v102, v103
	v_fmamk_f32 v104, v104, 0x3e38aa3b, v47
	v_fmamk_f32 v105, v105, 0x3e38aa3b, v47
	s_waitcnt lgkmcnt(7)
	v_mfma_f32_32x32x16_bf16 v[64:79], v[34:37], v[38:41], v[64:79]
	v_fmamk_f32 v106, v106, 0x3e38aa3b, v47
	v_fmamk_f32 v107, v107, 0x3e38aa3b, v47
	v_fmamk_f32 v108, v108, 0x3e38aa3b, v47
	v_fmamk_f32 v109, v109, 0x3e38aa3b, v47
	v_fmamk_f32 v110, v110, 0x3e38aa3b, v47
	v_fmamk_f32 v111, v111, 0x3e38aa3b, v47
	v_exp_f32_e32 v104, v104
	s_waitcnt lgkmcnt(6)
	v_mfma_f32_32x32x16_bf16 v[48:63], v[42:45], v[38:41], v[48:63]
	v_exp_f32_e32 v105, v105
	v_exp_f32_e32 v106, v106
	v_mfma_f32_32x32x16_bf16 v[80:95], v[176:179], v[38:41], v[80:95]
	v_exp_f32_e32 v107, v107
	v_exp_f32_e32 v108, v108
	v_exp_f32_e32 v109, v109
	v_exp_f32_e32 v110, v110
	v_exp_f32_e32 v111, v111
	v_cvt_pk_bf16_f32 v38, v104, v105
	v_cvt_pk_bf16_f32 v39, v106, v107
	v_cvt_pk_bf16_f32 v40, v108, v109
	v_cvt_pk_bf16_f32 v41, v110, v111
	v_fmamk_f32 v112, v112, 0x3e38aa3b, v47
	v_fmamk_f32 v113, v113, 0x3e38aa3b, v47
	s_waitcnt lgkmcnt(5)
	v_mfma_f32_32x32x16_bf16 v[64:79], v[218:221], v[38:41], v[64:79]
	v_fmamk_f32 v114, v114, 0x3e38aa3b, v47
	v_fmamk_f32 v115, v115, 0x3e38aa3b, v47
	v_fmamk_f32 v116, v116, 0x3e38aa3b, v47
	v_fmamk_f32 v117, v117, 0x3e38aa3b, v47
	v_fmamk_f32 v118, v118, 0x3e38aa3b, v47
	v_fmamk_f32 v119, v119, 0x3e38aa3b, v47
	v_exp_f32_e32 v112, v112
	s_waitcnt lgkmcnt(4)
	v_mfma_f32_32x32x16_bf16 v[48:63], v[222:225], v[38:41], v[48:63]
	v_exp_f32_e32 v113, v113
	v_exp_f32_e32 v114, v114
	v_mfma_f32_32x32x16_bf16 v[80:95], v[176:179], v[38:41], v[80:95]
	v_exp_f32_e32 v115, v115
	v_exp_f32_e32 v116, v116
	v_exp_f32_e32 v117, v117
	v_exp_f32_e32 v118, v118
	v_exp_f32_e32 v119, v119
	v_cvt_pk_bf16_f32 v38, v112, v113
	v_cvt_pk_bf16_f32 v39, v114, v115
	v_cvt_pk_bf16_f32 v40, v116, v117
	v_cvt_pk_bf16_f32 v41, v118, v119
	v_fmamk_f32 v120, v120, 0x3e38aa3b, v47
	v_fmamk_f32 v121, v121, 0x3e38aa3b, v47
	s_waitcnt lgkmcnt(3)
	v_mfma_f32_32x32x16_bf16 v[64:79], v[226:229], v[38:41], v[64:79]
	v_fmamk_f32 v122, v122, 0x3e38aa3b, v47
	v_fmamk_f32 v123, v123, 0x3e38aa3b, v47
	v_fmamk_f32 v124, v124, 0x3e38aa3b, v47
	v_fmamk_f32 v125, v125, 0x3e38aa3b, v47
	v_fmamk_f32 v126, v126, 0x3e38aa3b, v47
	v_fmamk_f32 v127, v127, 0x3e38aa3b, v47
	v_exp_f32_e32 v120, v120
	s_waitcnt lgkmcnt(2)
	v_mfma_f32_32x32x16_bf16 v[48:63], v[234:237], v[38:41], v[48:63]
	v_exp_f32_e32 v121, v121
	v_exp_f32_e32 v122, v122
	v_mfma_f32_32x32x16_bf16 v[80:95], v[176:179], v[38:41], v[80:95]
	v_exp_f32_e32 v123, v123
	v_exp_f32_e32 v124, v124
	v_exp_f32_e32 v125, v125
	v_exp_f32_e32 v126, v126
	v_exp_f32_e32 v127, v127
	v_cvt_pk_bf16_f32 v38, v120, v121
	v_cvt_pk_bf16_f32 v39, v122, v123
	v_cvt_pk_bf16_f32 v40, v124, v125
	v_cvt_pk_bf16_f32 v41, v126, v127
	s_nop 1
	s_waitcnt lgkmcnt(1)
	v_mfma_f32_32x32x16_bf16 v[64:79], v[238:241], v[38:41], v[64:79]
	s_waitcnt lgkmcnt(0)
	v_mfma_f32_32x32x16_bf16 v[48:63], v[242:245], v[38:41], v[48:63]
	v_mfma_f32_32x32x16_bf16 v[80:95], v[176:179], v[38:41], v[80:95]
	s_branch .LBB0_640
